# first grid seam: 8 per-XCC arrival counters in separate cache lines, pollers sum them (was one shared counter word)
# speedup vs baseline: 1.0060x; 1.0060x over previous
.LBB0_123:
	s_or_b64 exec, exec, s[4:5]
	s_cmp_lt_i32 s69, 2
	s_cbranch_scc1 .LBB0_135
	s_waitcnt vmcnt(0) lgkmcnt(0)
	s_barrier
	s_and_saveexec_b64 s[4:5], s[10:11]
	s_cbranch_execz .Lgs_join
	buffer_wbl2 sc1
	s_waitcnt vmcnt(0)
	s_lshl_b32 s6, s33, 8
	v_mov_b32_e32 v1, s6
	v_mov_b32_e32 v2, 1
	v_mov_b32_e32 v16, 0
	global_atomic_add v1, v2, s[34:35] offset:1152
	s_load_dword s6, s[0:1], 0xb8
	s_waitcnt lgkmcnt(0)
.Lgs_spin:
	global_load_dword v8, v16, s[34:35] offset:1152 sc1
	global_load_dword v9, v16, s[34:35] offset:1408 sc1
	global_load_dword v10, v16, s[34:35] offset:1664 sc1
	global_load_dword v11, v16, s[34:35] offset:1920 sc1
	global_load_dword v12, v16, s[34:35] offset:2176 sc1
	global_load_dword v13, v16, s[34:35] offset:2432 sc1
	global_load_dword v14, v16, s[34:35] offset:2688 sc1
	global_load_dword v15, v16, s[34:35] offset:2944 sc1
	s_waitcnt vmcnt(0)
	v_add3_u32 v8, v8, v9, v10
	v_add3_u32 v11, v11, v12, v13
	v_add3_u32 v8, v8, v14, v15
	v_add_u32_e32 v8, v8, v11
	s_nop 0
	v_readfirstlane_b32 s7, v8
	s_cmp_lt_u32 s7, s6
	s_cbranch_scc0 .Lgs_done
	s_sleep 1
	s_branch .Lgs_spin
